# gate/up SwiGLU epilogue rewritten by hand: batched exp/rcp (no trans-hazard nops), r*r and r*-log2e folded per row, saddr stores with 32-bit offsets; same f32 math + cvt_pk_bf16
# baseline (speedup 1.0000x reference)
; __device__ __forceinline__ unsigned cvt_pk_bf16(float lo, float hi) { unsigned r; asm volatile("v_cvt_pk_bf16_f32 %0, %1, %2" : "=v"(r) : "v"(lo), "v"(hi)); return r; }
; __device__ __forceinline__ float sigmoid_f(float v) { return __builtin_amdgcn_rcpf(1.0f + __expf(-v)); }
;     __device__ __forceinline__ void operator()(const f32x4 (&acc)[2][2][4][2], const Unit& u, int wr, int wc, int fr, int fq) const {
;     ...
; #pragma unroll
;         for (int ai = 0; ai < 2; ++ai)
; #pragma unroll
;             for (int m = 0; m < 4; ++m) { const int row = row0 + ai * HALF + m * 16; const float r = rr[ai][m];
;                 float o[8];
; #pragma unroll
;                 for (int n = 0; n < 2; ++n)
; #pragma unroll
;                     for (int j = 0; j < 4; ++j) { const float g = acc[ai][0][m][n][j] * r, up = acc[ai][1][m][n][j] * r; o[4 * n + j] = g * sigmoid_f(g) * up; }
;                 u32x4 w; w.x = cvt_pk_bf16(o[0], o[1]); w.y = cvt_pk_bf16(o[2], o[3]); w.z = cvt_pk_bf16(o[4], o[5]); w.w = cvt_pk_bf16(o[6], o[7]);
;                 *(u32x4*)(O + (size_t)row * D_FF + col0) = w; }
.LBB0_666:
	v_lshl_or_b32 v143, s51, 7, v161
	v_lshlrev_b32_e32 v143, 1, v143
	v_mad_u32_u24 v143, v142, s76, v143
	v_mul_f32_e32 v156, 0xbfb8aa3b, v151
	v_mul_f32_e32 v157, v151, v151
	v_mul_f32_e32 v152, v126, v156
	v_mul_f32_e32 v153, v127, v156
	v_mul_f32_e32 v154, v128, v156
	v_mul_f32_e32 v155, v129, v156
	v_exp_f32_e32 v152, v152
	v_exp_f32_e32 v153, v153
	v_exp_f32_e32 v154, v154
	v_exp_f32_e32 v155, v155
	v_mul_f32_e32 v122, v126, v122
	v_mul_f32_e32 v123, v127, v123
	v_mul_f32_e32 v124, v128, v124
	v_mul_f32_e32 v125, v129, v125
	v_add_f32_e32 v152, 1.0, v152
	v_add_f32_e32 v153, 1.0, v153
	v_add_f32_e32 v154, 1.0, v154
	v_add_f32_e32 v155, 1.0, v155
	v_rcp_f32_e32 v152, v152
	v_rcp_f32_e32 v153, v153
	v_rcp_f32_e32 v154, v154
	v_rcp_f32_e32 v155, v155
	v_mul_f32_e32 v152, v152, v157
	v_mul_f32_e32 v153, v153, v157
	v_mul_f32_e32 v154, v154, v157
	v_mul_f32_e32 v155, v155, v157
	v_mul_f32_e32 v122, v122, v152
	v_mul_f32_e32 v123, v123, v153
	v_mul_f32_e32 v124, v124, v154
	v_mul_f32_e32 v125, v125, v155
	v_mul_f32_e32 v152, v118, v156
	v_mul_f32_e32 v153, v119, v156
	v_mul_f32_e32 v154, v120, v156
	v_mul_f32_e32 v155, v121, v156
	v_exp_f32_e32 v152, v152
	v_exp_f32_e32 v153, v153
	v_exp_f32_e32 v154, v154
	v_exp_f32_e32 v155, v155
	v_mul_f32_e32 v114, v118, v114
	v_mul_f32_e32 v115, v119, v115
	v_mul_f32_e32 v116, v120, v116
	v_mul_f32_e32 v117, v121, v117
	v_add_f32_e32 v152, 1.0, v152
	v_add_f32_e32 v153, 1.0, v153
	v_add_f32_e32 v154, 1.0, v154
	v_add_f32_e32 v155, 1.0, v155
	v_rcp_f32_e32 v152, v152
	v_rcp_f32_e32 v153, v153
	v_rcp_f32_e32 v154, v154
	v_rcp_f32_e32 v155, v155
	v_mul_f32_e32 v152, v152, v157
	v_mul_f32_e32 v153, v153, v157
	v_mul_f32_e32 v154, v154, v157
	v_mul_f32_e32 v155, v155, v157
	v_mul_f32_e32 v114, v114, v152
	v_mul_f32_e32 v115, v115, v153
	v_mul_f32_e32 v116, v116, v154
	v_mul_f32_e32 v117, v117, v155
	v_cvt_pk_bf16_f32 v126, v122, v123
	v_cvt_pk_bf16_f32 v127, v124, v125
	v_cvt_pk_bf16_f32 v128, v114, v115
	v_cvt_pk_bf16_f32 v129, v116, v117
	global_store_dwordx4 v143, v[126:129], s[10:11]
	v_mul_f32_e32 v156, 0xbfb8aa3b, v150
	v_mul_f32_e32 v157, v150, v150
	v_mul_f32_e32 v152, v110, v156
	v_mul_f32_e32 v153, v111, v156
	v_mul_f32_e32 v154, v112, v156
	v_mul_f32_e32 v155, v113, v156
	v_exp_f32_e32 v152, v152
	v_exp_f32_e32 v153, v153
	v_exp_f32_e32 v154, v154
	v_exp_f32_e32 v155, v155
	v_mul_f32_e32 v106, v110, v106
	v_mul_f32_e32 v107, v111, v107
	v_mul_f32_e32 v108, v112, v108
	v_mul_f32_e32 v109, v113, v109
	v_add_f32_e32 v152, 1.0, v152
	v_add_f32_e32 v153, 1.0, v153
	v_add_f32_e32 v154, 1.0, v154
	v_add_f32_e32 v155, 1.0, v155
	v_rcp_f32_e32 v152, v152
	v_rcp_f32_e32 v153, v153
	v_rcp_f32_e32 v154, v154
	v_rcp_f32_e32 v155, v155
	v_mul_f32_e32 v152, v152, v157
	v_mul_f32_e32 v153, v153, v157
	v_mul_f32_e32 v154, v154, v157
	v_mul_f32_e32 v155, v155, v157
	v_mul_f32_e32 v106, v106, v152
	v_mul_f32_e32 v107, v107, v153
	v_mul_f32_e32 v108, v108, v154
	v_mul_f32_e32 v109, v109, v155
	v_mul_f32_e32 v152, v102, v156
	v_mul_f32_e32 v153, v103, v156
	v_mul_f32_e32 v154, v104, v156
	v_mul_f32_e32 v155, v105, v156
	v_exp_f32_e32 v152, v152
	v_exp_f32_e32 v153, v153
	v_exp_f32_e32 v154, v154
	v_exp_f32_e32 v155, v155
	v_mul_f32_e32 v98, v102, v98
	v_mul_f32_e32 v99, v103, v99
	v_mul_f32_e32 v100, v104, v100
	v_mul_f32_e32 v101, v105, v101
	v_add_f32_e32 v152, 1.0, v152
	v_add_f32_e32 v153, 1.0, v153
	v_add_f32_e32 v154, 1.0, v154
	v_add_f32_e32 v155, 1.0, v155
	v_rcp_f32_e32 v152, v152
	v_rcp_f32_e32 v153, v153
	v_rcp_f32_e32 v154, v154
	v_rcp_f32_e32 v155, v155
	v_mul_f32_e32 v152, v152, v157
	v_mul_f32_e32 v153, v153, v157
	v_mul_f32_e32 v154, v154, v157
	v_mul_f32_e32 v155, v155, v157
	v_mul_f32_e32 v98, v98, v152
	v_mul_f32_e32 v99, v99, v153
	v_mul_f32_e32 v100, v100, v154
	v_mul_f32_e32 v101, v101, v155
	v_cvt_pk_bf16_f32 v110, v106, v107
	v_cvt_pk_bf16_f32 v111, v108, v109
	v_cvt_pk_bf16_f32 v112, v98, v99
	v_cvt_pk_bf16_f32 v113, v100, v101
	v_add_u32_e32 v142, 0x2c000, v143
	global_store_dwordx4 v142, v[110:113], s[10:11]
	v_mul_f32_e32 v156, 0xbfb8aa3b, v149
	v_mul_f32_e32 v157, v149, v149
	v_mul_f32_e32 v152, v94, v156
	v_mul_f32_e32 v153, v95, v156
	v_mul_f32_e32 v154, v96, v156
	v_mul_f32_e32 v155, v97, v156
	v_exp_f32_e32 v152, v152
	v_exp_f32_e32 v153, v153
	v_exp_f32_e32 v154, v154
	v_exp_f32_e32 v155, v155
	v_mul_f32_e32 v90, v94, v90
	v_mul_f32_e32 v91, v95, v91
	v_mul_f32_e32 v92, v96, v92
	v_mul_f32_e32 v93, v97, v93
	v_add_f32_e32 v152, 1.0, v152
	v_add_f32_e32 v153, 1.0, v153
	v_add_f32_e32 v154, 1.0, v154
	v_add_f32_e32 v155, 1.0, v155
	v_rcp_f32_e32 v152, v152
	v_rcp_f32_e32 v153, v153
	v_rcp_f32_e32 v154, v154
	v_rcp_f32_e32 v155, v155
	v_mul_f32_e32 v152, v152, v157
	v_mul_f32_e32 v153, v153, v157
	v_mul_f32_e32 v154, v154, v157
	v_mul_f32_e32 v155, v155, v157
	v_mul_f32_e32 v90, v90, v152
	v_mul_f32_e32 v91, v91, v153
	v_mul_f32_e32 v92, v92, v154
	v_mul_f32_e32 v93, v93, v155
	v_mul_f32_e32 v152, v86, v156
	v_mul_f32_e32 v153, v87, v156
	v_mul_f32_e32 v154, v88, v156
	v_mul_f32_e32 v155, v89, v156
	v_exp_f32_e32 v152, v152
	v_exp_f32_e32 v153, v153
	v_exp_f32_e32 v154, v154
	v_exp_f32_e32 v155, v155
	v_mul_f32_e32 v82, v86, v82
	v_mul_f32_e32 v83, v87, v83
	v_mul_f32_e32 v84, v88, v84
	v_mul_f32_e32 v85, v89, v85
	v_add_f32_e32 v152, 1.0, v152
	v_add_f32_e32 v153, 1.0, v153
	v_add_f32_e32 v154, 1.0, v154
	v_add_f32_e32 v155, 1.0, v155
	v_rcp_f32_e32 v152, v152
	v_rcp_f32_e32 v153, v153
	v_rcp_f32_e32 v154, v154
	v_rcp_f32_e32 v155, v155
	v_mul_f32_e32 v152, v152, v157
	v_mul_f32_e32 v153, v153, v157
	v_mul_f32_e32 v154, v154, v157
	v_mul_f32_e32 v155, v155, v157
; __device__ __forceinline__ unsigned cvt_pk_bf16(float lo, float hi) { unsigned r; asm volatile("v_cvt_pk_bf16_f32 %0, %1, %2" : "=v"(r) : "v"(lo), "v"(hi)); return r; }
; __device__ __forceinline__ float sigmoid_f(float v) { return __builtin_amdgcn_rcpf(1.0f + __expf(-v)); }
;     __device__ __forceinline__ void operator()(const f32x4 (&acc)[2][2][4][2], const Unit& u, int wr, int wc, int fr, int fq) const {
;     ...
;             for (int m = 0; m < 4; ++m) { const int row = row0 + ai * HALF + m * 16; const float r = rr[ai][m];
;                 float o[8];
; #pragma unroll
;                 for (int n = 0; n < 2; ++n)
; #pragma unroll
;                     for (int j = 0; j < 4; ++j) { const float g = acc[ai][0][m][n][j] * r, up = acc[ai][1][m][n][j] * r; o[4 * n + j] = g * sigmoid_f(g) * up; }
;                 u32x4 w; w.x = cvt_pk_bf16(o[0], o[1]); w.y = cvt_pk_bf16(o[2], o[3]); w.z = cvt_pk_bf16(o[4], o[5]); w.w = cvt_pk_bf16(o[6], o[7]);
;                 *(u32x4*)(O + (size_t)row * D_FF + col0) = w; }
	v_mul_f32_e32 v82, v82, v152
	v_mul_f32_e32 v83, v83, v153
	v_mul_f32_e32 v84, v84, v154
	v_mul_f32_e32 v85, v85, v155
	v_cvt_pk_bf16_f32 v94, v90, v91
	v_cvt_pk_bf16_f32 v95, v92, v93
	v_cvt_pk_bf16_f32 v96, v82, v83
	v_cvt_pk_bf16_f32 v97, v84, v85
	v_add_u32_e32 v142, 0x58000, v143
	global_store_dwordx4 v142, v[94:97], s[10:11]
	v_mul_f32_e32 v156, 0xbfb8aa3b, v148
	v_mul_f32_e32 v157, v148, v148
	v_mul_f32_e32 v152, v78, v156
	v_mul_f32_e32 v153, v79, v156
	v_mul_f32_e32 v154, v80, v156
	v_mul_f32_e32 v155, v81, v156
	v_exp_f32_e32 v152, v152
	v_exp_f32_e32 v153, v153
	v_exp_f32_e32 v154, v154
	v_exp_f32_e32 v155, v155
	v_mul_f32_e32 v74, v78, v74
	v_mul_f32_e32 v75, v79, v75
	v_mul_f32_e32 v76, v80, v76
	v_mul_f32_e32 v77, v81, v77
	v_add_f32_e32 v152, 1.0, v152
	v_add_f32_e32 v153, 1.0, v153
	v_add_f32_e32 v154, 1.0, v154
	v_add_f32_e32 v155, 1.0, v155
	v_rcp_f32_e32 v152, v152
	v_rcp_f32_e32 v153, v153
	v_rcp_f32_e32 v154, v154
	v_rcp_f32_e32 v155, v155
	v_mul_f32_e32 v152, v152, v157
	v_mul_f32_e32 v153, v153, v157
	v_mul_f32_e32 v154, v154, v157
	v_mul_f32_e32 v155, v155, v157
	v_mul_f32_e32 v74, v74, v152
	v_mul_f32_e32 v75, v75, v153
	v_mul_f32_e32 v76, v76, v154
	v_mul_f32_e32 v77, v77, v155
	v_mul_f32_e32 v152, v70, v156
	v_mul_f32_e32 v153, v71, v156
	v_mul_f32_e32 v154, v72, v156
	v_mul_f32_e32 v155, v73, v156
	v_exp_f32_e32 v152, v152
	v_exp_f32_e32 v153, v153
	v_exp_f32_e32 v154, v154
	v_exp_f32_e32 v155, v155
	v_mul_f32_e32 v66, v70, v66
	v_mul_f32_e32 v67, v71, v67
	v_mul_f32_e32 v68, v72, v68
	v_mul_f32_e32 v69, v73, v69
	v_add_f32_e32 v152, 1.0, v152
	v_add_f32_e32 v153, 1.0, v153
	v_add_f32_e32 v154, 1.0, v154
	v_add_f32_e32 v155, 1.0, v155
	v_rcp_f32_e32 v152, v152
	v_rcp_f32_e32 v153, v153
	v_rcp_f32_e32 v154, v154
	v_rcp_f32_e32 v155, v155
	v_mul_f32_e32 v152, v152, v157
	v_mul_f32_e32 v153, v153, v157
	v_mul_f32_e32 v154, v154, v157
	v_mul_f32_e32 v155, v155, v157
	v_mul_f32_e32 v66, v66, v152
	v_mul_f32_e32 v67, v67, v153
	v_mul_f32_e32 v68, v68, v154
	v_mul_f32_e32 v69, v69, v155
	v_cvt_pk_bf16_f32 v78, v74, v75
	v_cvt_pk_bf16_f32 v79, v76, v77
	v_cvt_pk_bf16_f32 v80, v66, v67
	v_cvt_pk_bf16_f32 v81, v68, v69
	v_add_u32_e32 v142, 0x84000, v143
	global_store_dwordx4 v142, v[78:81], s[10:11]
	v_mul_f32_e32 v156, 0xbfb8aa3b, v147
	v_mul_f32_e32 v157, v147, v147
	v_mul_f32_e32 v152, v62, v156
	v_mul_f32_e32 v153, v63, v156
	v_mul_f32_e32 v154, v64, v156
	v_mul_f32_e32 v155, v65, v156
	v_exp_f32_e32 v152, v152
	v_exp_f32_e32 v153, v153
	v_exp_f32_e32 v154, v154
	v_exp_f32_e32 v155, v155
	v_mul_f32_e32 v58, v62, v58
	v_mul_f32_e32 v59, v63, v59
	v_mul_f32_e32 v60, v64, v60
	v_mul_f32_e32 v61, v65, v61
	v_add_f32_e32 v152, 1.0, v152
	v_add_f32_e32 v153, 1.0, v153
	v_add_f32_e32 v154, 1.0, v154
	v_add_f32_e32 v155, 1.0, v155
	v_rcp_f32_e32 v152, v152
	v_rcp_f32_e32 v153, v153
	v_rcp_f32_e32 v154, v154
	v_rcp_f32_e32 v155, v155
	v_mul_f32_e32 v152, v152, v157
	v_mul_f32_e32 v153, v153, v157
	v_mul_f32_e32 v154, v154, v157
	v_mul_f32_e32 v155, v155, v157
	v_mul_f32_e32 v58, v58, v152
	v_mul_f32_e32 v59, v59, v153
	v_mul_f32_e32 v60, v60, v154
	v_mul_f32_e32 v61, v61, v155
	v_mul_f32_e32 v152, v54, v156
	v_mul_f32_e32 v153, v55, v156
	v_mul_f32_e32 v154, v56, v156
	v_mul_f32_e32 v155, v57, v156
	v_exp_f32_e32 v152, v152
	v_exp_f32_e32 v153, v153
	v_exp_f32_e32 v154, v154
	v_exp_f32_e32 v155, v155
	v_mul_f32_e32 v50, v54, v50
	v_mul_f32_e32 v51, v55, v51
	v_mul_f32_e32 v52, v56, v52
	v_mul_f32_e32 v53, v57, v53
	v_add_f32_e32 v152, 1.0, v152
	v_add_f32_e32 v153, 1.0, v153
	v_add_f32_e32 v154, 1.0, v154
	v_add_f32_e32 v155, 1.0, v155
	v_rcp_f32_e32 v152, v152
	v_rcp_f32_e32 v153, v153
	v_rcp_f32_e32 v154, v154
	v_rcp_f32_e32 v155, v155
	v_mul_f32_e32 v152, v152, v157
	v_mul_f32_e32 v153, v153, v157
	v_mul_f32_e32 v154, v154, v157
	v_mul_f32_e32 v155, v155, v157
	v_mul_f32_e32 v50, v50, v152
	v_mul_f32_e32 v51, v51, v153
	v_mul_f32_e32 v52, v52, v154
	v_mul_f32_e32 v53, v53, v155
	v_cvt_pk_bf16_f32 v62, v58, v59
	v_cvt_pk_bf16_f32 v63, v60, v61
	v_cvt_pk_bf16_f32 v64, v50, v51
	v_cvt_pk_bf16_f32 v65, v52, v53
	v_add_u32_e32 v142, 0x160000, v143
	global_store_dwordx4 v142, v[62:65], s[10:11]
	v_mul_f32_e32 v156, 0xbfb8aa3b, v146
	v_mul_f32_e32 v157, v146, v146
	v_mul_f32_e32 v152, v46, v156
	v_mul_f32_e32 v153, v47, v156
	v_mul_f32_e32 v154, v48, v156
	v_mul_f32_e32 v155, v49, v156
	v_exp_f32_e32 v152, v152
	v_exp_f32_e32 v153, v153
	v_exp_f32_e32 v154, v154
	v_exp_f32_e32 v155, v155
	v_mul_f32_e32 v42, v46, v42
	v_mul_f32_e32 v43, v47, v43
	v_mul_f32_e32 v44, v48, v44
	v_mul_f32_e32 v45, v49, v45
	v_add_f32_e32 v152, 1.0, v152
	v_add_f32_e32 v153, 1.0, v153
	v_add_f32_e32 v154, 1.0, v154
	v_add_f32_e32 v155, 1.0, v155
	v_rcp_f32_e32 v152, v152
	v_rcp_f32_e32 v153, v153
	v_rcp_f32_e32 v154, v154
	v_rcp_f32_e32 v155, v155
	v_mul_f32_e32 v152, v152, v157
	v_mul_f32_e32 v153, v153, v157
	v_mul_f32_e32 v154, v154, v157
	v_mul_f32_e32 v155, v155, v157
	v_mul_f32_e32 v42, v42, v152
	v_mul_f32_e32 v43, v43, v153
	v_mul_f32_e32 v44, v44, v154
; __device__ __forceinline__ unsigned cvt_pk_bf16(float lo, float hi) { unsigned r; asm volatile("v_cvt_pk_bf16_f32 %0, %1, %2" : "=v"(r) : "v"(lo), "v"(hi)); return r; }
; __device__ __forceinline__ float sigmoid_f(float v) { return __builtin_amdgcn_rcpf(1.0f + __expf(-v)); }
;     __device__ __forceinline__ void operator()(const f32x4 (&acc)[2][2][4][2], const Unit& u, int wr, int wc, int fr, int fq) const {
;     ...
;             for (int m = 0; m < 4; ++m) { const int row = row0 + ai * HALF + m * 16; const float r = rr[ai][m];
;                 float o[8];
; #pragma unroll
;                 for (int n = 0; n < 2; ++n)
; #pragma unroll
;                     for (int j = 0; j < 4; ++j) { const float g = acc[ai][0][m][n][j] * r, up = acc[ai][1][m][n][j] * r; o[4 * n + j] = g * sigmoid_f(g) * up; }
;                 u32x4 w; w.x = cvt_pk_bf16(o[0], o[1]); w.y = cvt_pk_bf16(o[2], o[3]); w.z = cvt_pk_bf16(o[4], o[5]); w.w = cvt_pk_bf16(o[6], o[7]);
;                 *(u32x4*)(O + (size_t)row * D_FF + col0) = w; }
; template <class Epi, class Sched, bool ALIGN_EPI = false, bool SP2 = false>
; __device__ __forceinline__ void gemm_phase(PG8_LAS unsigned char* lds, const Gemm g, const Sched& S, const Epi& E) {
;     ...
;         if constexpr (!Epi::AFTER_DRAIN) { E(acc, cur, wr, wc, fr, fq); S.done(cur); }
;         if (!has_next) break;
	v_mul_f32_e32 v45, v45, v155
	v_mul_f32_e32 v152, v38, v156
	v_mul_f32_e32 v153, v39, v156
	v_mul_f32_e32 v154, v40, v156
	v_mul_f32_e32 v155, v41, v156
	v_exp_f32_e32 v152, v152
	v_exp_f32_e32 v153, v153
	v_exp_f32_e32 v154, v154
	v_exp_f32_e32 v155, v155
	v_mul_f32_e32 v34, v38, v34
	v_mul_f32_e32 v35, v39, v35
	v_mul_f32_e32 v36, v40, v36
	v_mul_f32_e32 v37, v41, v37
	v_add_f32_e32 v152, 1.0, v152
	v_add_f32_e32 v153, 1.0, v153
	v_add_f32_e32 v154, 1.0, v154
	v_add_f32_e32 v155, 1.0, v155
	v_rcp_f32_e32 v152, v152
	v_rcp_f32_e32 v153, v153
	v_rcp_f32_e32 v154, v154
	v_rcp_f32_e32 v155, v155
	v_mul_f32_e32 v152, v152, v157
	v_mul_f32_e32 v153, v153, v157
	v_mul_f32_e32 v154, v154, v157
	v_mul_f32_e32 v155, v155, v157
	v_mul_f32_e32 v34, v34, v152
	v_mul_f32_e32 v35, v35, v153
	v_mul_f32_e32 v36, v36, v154
	v_mul_f32_e32 v37, v37, v155
	v_cvt_pk_bf16_f32 v46, v42, v43
	v_cvt_pk_bf16_f32 v47, v44, v45
	v_cvt_pk_bf16_f32 v48, v34, v35
	v_cvt_pk_bf16_f32 v49, v36, v37
	v_add_u32_e32 v142, 0x18c000, v143
	global_store_dwordx4 v142, v[46:49], s[10:11]
	v_mul_f32_e32 v156, 0xbfb8aa3b, v145
	v_mul_f32_e32 v157, v145, v145
	v_mul_f32_e32 v152, v30, v156
	v_mul_f32_e32 v153, v31, v156
	v_mul_f32_e32 v154, v32, v156
	v_mul_f32_e32 v155, v33, v156
	v_exp_f32_e32 v152, v152
	v_exp_f32_e32 v153, v153
	v_exp_f32_e32 v154, v154
	v_exp_f32_e32 v155, v155
	v_mul_f32_e32 v26, v30, v26
	v_mul_f32_e32 v27, v31, v27
	v_mul_f32_e32 v28, v32, v28
	v_mul_f32_e32 v29, v33, v29
	v_add_f32_e32 v152, 1.0, v152
	v_add_f32_e32 v153, 1.0, v153
	v_add_f32_e32 v154, 1.0, v154
	v_add_f32_e32 v155, 1.0, v155
	v_rcp_f32_e32 v152, v152
	v_rcp_f32_e32 v153, v153
	v_rcp_f32_e32 v154, v154
	v_rcp_f32_e32 v155, v155
	v_mul_f32_e32 v152, v152, v157
	v_mul_f32_e32 v153, v153, v157
	v_mul_f32_e32 v154, v154, v157
	v_mul_f32_e32 v155, v155, v157
	v_mul_f32_e32 v26, v26, v152
	v_mul_f32_e32 v27, v27, v153
	v_mul_f32_e32 v28, v28, v154
	v_mul_f32_e32 v29, v29, v155
	v_mul_f32_e32 v152, v22, v156
	v_mul_f32_e32 v153, v23, v156
	v_mul_f32_e32 v154, v24, v156
	v_mul_f32_e32 v155, v25, v156
	v_exp_f32_e32 v152, v152
	v_exp_f32_e32 v153, v153
	v_exp_f32_e32 v154, v154
	v_exp_f32_e32 v155, v155
	v_mul_f32_e32 v18, v22, v18
	v_mul_f32_e32 v19, v23, v19
	v_mul_f32_e32 v20, v24, v20
	v_mul_f32_e32 v21, v25, v21
	v_add_f32_e32 v152, 1.0, v152
	v_add_f32_e32 v153, 1.0, v153
	v_add_f32_e32 v154, 1.0, v154
	v_add_f32_e32 v155, 1.0, v155
	v_rcp_f32_e32 v152, v152
	v_rcp_f32_e32 v153, v153
	v_rcp_f32_e32 v154, v154
	v_rcp_f32_e32 v155, v155
	v_mul_f32_e32 v152, v152, v157
	v_mul_f32_e32 v153, v153, v157
	v_mul_f32_e32 v154, v154, v157
	v_mul_f32_e32 v155, v155, v157
	v_mul_f32_e32 v18, v18, v152
	v_mul_f32_e32 v19, v19, v153
	v_mul_f32_e32 v20, v20, v154
	v_mul_f32_e32 v21, v21, v155
	v_cvt_pk_bf16_f32 v30, v26, v27
	v_cvt_pk_bf16_f32 v31, v28, v29
	v_cvt_pk_bf16_f32 v32, v18, v19
	v_cvt_pk_bf16_f32 v33, v20, v21
	v_add_u32_e32 v142, 0x1b8000, v143
	global_store_dwordx4 v142, v[30:33], s[10:11]
	v_mul_f32_e32 v156, 0xbfb8aa3b, v144
	v_mul_f32_e32 v157, v144, v144
	v_mul_f32_e32 v152, v14, v156
	v_mul_f32_e32 v153, v15, v156
	v_mul_f32_e32 v154, v16, v156
	v_mul_f32_e32 v155, v17, v156
	v_exp_f32_e32 v152, v152
	v_exp_f32_e32 v153, v153
	v_exp_f32_e32 v154, v154
	v_exp_f32_e32 v155, v155
	v_mul_f32_e32 v10, v14, v10
	v_mul_f32_e32 v11, v15, v11
	v_mul_f32_e32 v12, v16, v12
	v_mul_f32_e32 v13, v17, v13
	v_add_f32_e32 v152, 1.0, v152
	v_add_f32_e32 v153, 1.0, v153
	v_add_f32_e32 v154, 1.0, v154
	v_add_f32_e32 v155, 1.0, v155
	v_rcp_f32_e32 v152, v152
	v_rcp_f32_e32 v153, v153
	v_rcp_f32_e32 v154, v154
	v_rcp_f32_e32 v155, v155
	v_mul_f32_e32 v152, v152, v157
	v_mul_f32_e32 v153, v153, v157
	v_mul_f32_e32 v154, v154, v157
	v_mul_f32_e32 v155, v155, v157
	v_mul_f32_e32 v10, v10, v152
	v_mul_f32_e32 v11, v11, v153
	v_mul_f32_e32 v12, v12, v154
	v_mul_f32_e32 v13, v13, v155
	v_mul_f32_e32 v152, v6, v156
	v_mul_f32_e32 v153, v7, v156
	v_mul_f32_e32 v154, v8, v156
	v_mul_f32_e32 v155, v9, v156
	v_exp_f32_e32 v152, v152
	v_exp_f32_e32 v153, v153
	v_exp_f32_e32 v154, v154
	v_exp_f32_e32 v155, v155
	v_mul_f32_e32 v2, v6, v2
	v_mul_f32_e32 v3, v7, v3
	v_mul_f32_e32 v4, v8, v4
	v_mul_f32_e32 v5, v9, v5
	v_add_f32_e32 v152, 1.0, v152
	v_add_f32_e32 v153, 1.0, v153
	v_add_f32_e32 v154, 1.0, v154
	v_add_f32_e32 v155, 1.0, v155
	v_rcp_f32_e32 v152, v152
	v_rcp_f32_e32 v153, v153
	v_rcp_f32_e32 v154, v154
	v_rcp_f32_e32 v155, v155
	v_mul_f32_e32 v152, v152, v157
	v_mul_f32_e32 v153, v153, v157
	v_mul_f32_e32 v154, v154, v157
	v_mul_f32_e32 v155, v155, v157
	v_mul_f32_e32 v2, v2, v152
	v_mul_f32_e32 v3, v3, v153
	v_mul_f32_e32 v4, v4, v154
	v_mul_f32_e32 v5, v5, v155
	v_cvt_pk_bf16_f32 v14, v10, v11
	v_cvt_pk_bf16_f32 v15, v12, v13
	v_cvt_pk_bf16_f32 v16, v2, v3
	v_cvt_pk_bf16_f32 v17, v4, v5
	v_add_u32_e32 v142, 0x1e4000, v143
	global_store_dwordx4 v142, v[14:17], s[10:11]
	s_andn2_b64 vcc, exec, s[40:41]
	s_mov_b64 s[16:17], -1
	s_cbranch_vccnz .LBB0_655
	s_andn2_b64 vcc, exec, s[6:7]
	s_cbranch_vccnz .LBB0_654
	s_barrier
	s_branch .LBB0_654
